# att14 = att10 + RG-LRU final-pass carry-in de-serialised: all tile-summary loads issued up front (one round trip instead of up to four), same fmac chain order
# speedup vs baseline: 1.0081x; 1.0081x over previous
.LBB0_457:
	s_or_b64 exec, exec, s[0:1]
	s_lshr_b32 s0, s17, 8
	s_cmp_eq_u32 s46, 0
	s_cbranch_scc1 .LBB0_460
	s_and_b32 s2, s56, 0xffffffe0
	s_ashr_i32 s3, s2, 31
	s_lshl_b64 s[2:3], s[2:3], 13
	s_add_u32 s2, s92, s2
	s_addc_u32 s3, s93, s3
	s_waitcnt vmcnt(0)
	v_lshlrev_b32_e32 v2, 2, v0
	v_add_u32_e32 v3, 0x1000, v2
	v_mov_b32_e32 v111, 0
	global_load_dword v191, v2, s[2:3]
	global_load_dword v192, v3, s[2:3]
	s_add_u32 s2, s2, 0x2000
	s_addc_u32 s3, s3, 0
	s_cmp_eq_u32 s46, 1
	s_cbranch_scc1 .Lci_loaded
	global_load_dword v193, v2, s[2:3]
	global_load_dword v194, v3, s[2:3]
	s_add_u32 s2, s2, 0x2000
	s_addc_u32 s3, s3, 0
	s_cmp_eq_u32 s46, 2
	s_cbranch_scc1 .Lci_loaded
	global_load_dword v195, v2, s[2:3]
	global_load_dword v196, v3, s[2:3]
	s_add_u32 s2, s2, 0x2000
	s_addc_u32 s3, s3, 0
	s_cmp_eq_u32 s46, 3
	s_cbranch_scc1 .Lci_loaded
	global_load_dword v197, v2, s[2:3]
	global_load_dword v198, v3, s[2:3]
	s_add_u32 s2, s2, 0x2000
	s_addc_u32 s3, s3, 0
	s_cmp_eq_u32 s46, 4
	s_cbranch_scc1 .Lci_loaded
	global_load_dword v199, v2, s[2:3]
	global_load_dword v200, v3, s[2:3]
	s_add_u32 s2, s2, 0x2000
	s_addc_u32 s3, s3, 0
	s_cmp_eq_u32 s46, 5
	s_cbranch_scc1 .Lci_loaded
	global_load_dword v201, v2, s[2:3]
	global_load_dword v202, v3, s[2:3]
	s_add_u32 s2, s2, 0x2000
	s_addc_u32 s3, s3, 0
	s_cmp_eq_u32 s46, 6
	s_cbranch_scc1 .Lci_loaded
	global_load_dword v203, v2, s[2:3]
	global_load_dword v204, v3, s[2:3]
	s_add_u32 s2, s2, 0x2000
	s_addc_u32 s3, s3, 0
	s_cmp_eq_u32 s46, 7
	s_cbranch_scc1 .Lci_loaded
	global_load_dword v205, v2, s[2:3]
	global_load_dword v206, v3, s[2:3]
	s_add_u32 s2, s2, 0x2000
	s_addc_u32 s3, s3, 0
	s_cmp_eq_u32 s46, 8
	s_cbranch_scc1 .Lci_loaded
	global_load_dword v207, v2, s[2:3]
	global_load_dword v208, v3, s[2:3]
	s_add_u32 s2, s2, 0x2000
	s_addc_u32 s3, s3, 0
	s_cmp_eq_u32 s46, 9
	s_cbranch_scc1 .Lci_loaded
	global_load_dword v209, v2, s[2:3]
	global_load_dword v210, v3, s[2:3]
	s_add_u32 s2, s2, 0x2000
	s_addc_u32 s3, s3, 0
	s_cmp_eq_u32 s46, 10
	s_cbranch_scc1 .Lci_loaded
	global_load_dword v211, v2, s[2:3]
	global_load_dword v212, v3, s[2:3]
	s_add_u32 s2, s2, 0x2000
	s_addc_u32 s3, s3, 0
	s_cmp_eq_u32 s46, 11
	s_cbranch_scc1 .Lci_loaded
	global_load_dword v213, v2, s[2:3]
	global_load_dword v214, v3, s[2:3]
	s_add_u32 s2, s2, 0x2000
	s_addc_u32 s3, s3, 0
	s_cmp_eq_u32 s46, 12
	s_cbranch_scc1 .Lci_loaded
	global_load_dword v215, v2, s[2:3]
	global_load_dword v216, v3, s[2:3]
	s_add_u32 s2, s2, 0x2000
	s_addc_u32 s3, s3, 0
	s_cmp_eq_u32 s46, 13
	s_cbranch_scc1 .Lci_loaded
	global_load_dword v217, v2, s[2:3]
	global_load_dword v218, v3, s[2:3]
	s_add_u32 s2, s2, 0x2000
	s_addc_u32 s3, s3, 0
	s_cmp_eq_u32 s46, 14
	s_cbranch_scc1 .Lci_loaded
	global_load_dword v219, v2, s[2:3]
	global_load_dword v220, v3, s[2:3]
	s_add_u32 s2, s2, 0x2000
	s_addc_u32 s3, s3, 0
	s_cmp_eq_u32 s46, 15
	s_cbranch_scc1 .Lci_loaded
	global_load_dword v221, v2, s[2:3]
	global_load_dword v222, v3, s[2:3]
	s_add_u32 s2, s2, 0x2000
	s_addc_u32 s3, s3, 0
	s_cmp_eq_u32 s46, 16
	s_cbranch_scc1 .Lci_loaded
	global_load_dword v223, v2, s[2:3]
	global_load_dword v224, v3, s[2:3]
	s_add_u32 s2, s2, 0x2000
	s_addc_u32 s3, s3, 0
	s_cmp_eq_u32 s46, 17
	s_cbranch_scc1 .Lci_loaded
	global_load_dword v225, v2, s[2:3]
	global_load_dword v226, v3, s[2:3]
	s_add_u32 s2, s2, 0x2000
	s_addc_u32 s3, s3, 0
	s_cmp_eq_u32 s46, 18
	s_cbranch_scc1 .Lci_loaded
	global_load_dword v227, v2, s[2:3]
	global_load_dword v228, v3, s[2:3]
	s_add_u32 s2, s2, 0x2000
	s_addc_u32 s3, s3, 0
	s_cmp_eq_u32 s46, 19
	s_cbranch_scc1 .Lci_loaded
	global_load_dword v229, v2, s[2:3]
	global_load_dword v230, v3, s[2:3]
	s_add_u32 s2, s2, 0x2000
	s_addc_u32 s3, s3, 0
	s_cmp_eq_u32 s46, 20
	s_cbranch_scc1 .Lci_loaded
	global_load_dword v231, v2, s[2:3]
	global_load_dword v232, v3, s[2:3]
	s_add_u32 s2, s2, 0x2000
	s_addc_u32 s3, s3, 0
	s_cmp_eq_u32 s46, 21
	s_cbranch_scc1 .Lci_loaded
	global_load_dword v233, v2, s[2:3]
	global_load_dword v234, v3, s[2:3]
	s_add_u32 s2, s2, 0x2000
	s_addc_u32 s3, s3, 0
	s_cmp_eq_u32 s46, 22
	s_cbranch_scc1 .Lci_loaded
	global_load_dword v235, v2, s[2:3]
	global_load_dword v236, v3, s[2:3]
	s_add_u32 s2, s2, 0x2000
	s_addc_u32 s3, s3, 0
	s_cmp_eq_u32 s46, 23
	s_cbranch_scc1 .Lci_loaded
	global_load_dword v237, v2, s[2:3]
	global_load_dword v238, v3, s[2:3]
	s_add_u32 s2, s2, 0x2000
	s_addc_u32 s3, s3, 0
	s_cmp_eq_u32 s46, 24
	s_cbranch_scc1 .Lci_loaded
	global_load_dword v239, v2, s[2:3]
	global_load_dword v240, v3, s[2:3]
	s_add_u32 s2, s2, 0x2000
	s_addc_u32 s3, s3, 0
	s_cmp_eq_u32 s46, 25
	s_cbranch_scc1 .Lci_loaded
	global_load_dword v241, v2, s[2:3]
	global_load_dword v242, v3, s[2:3]
	s_add_u32 s2, s2, 0x2000
	s_addc_u32 s3, s3, 0
	s_cmp_eq_u32 s46, 26
	s_cbranch_scc1 .Lci_loaded
	global_load_dword v243, v2, s[2:3]
	global_load_dword v8, v3, s[2:3]
	s_add_u32 s2, s2, 0x2000
	s_addc_u32 s3, s3, 0
	s_cmp_eq_u32 s46, 27
	s_cbranch_scc1 .Lci_loaded
	global_load_dword v247, v2, s[2:3]
	global_load_dword v248, v3, s[2:3]
	s_add_u32 s2, s2, 0x2000
	s_addc_u32 s3, s3, 0
	s_cmp_eq_u32 s46, 28
	s_cbranch_scc1 .Lci_loaded
	global_load_dword v249, v2, s[2:3]
	global_load_dword v250, v3, s[2:3]
	s_add_u32 s2, s2, 0x2000
	s_addc_u32 s3, s3, 0
	s_cmp_eq_u32 s46, 29
	s_cbranch_scc1 .Lci_loaded
	global_load_dword v251, v2, s[2:3]
	global_load_dword v252, v3, s[2:3]
	s_add_u32 s2, s2, 0x2000
	s_addc_u32 s3, s3, 0
	s_cmp_eq_u32 s46, 30
	s_cbranch_scc1 .Lci_loaded
	global_load_dword v253, v2, s[2:3]
	global_load_dword v255, v3, s[2:3]
.Lci_loaded:
	s_waitcnt vmcnt(0)
	v_fmac_f32_e32 v192, v111, v191
	s_cmp_eq_u32 s46, 1
	s_cbranch_scc1 .Lci_x0
	v_fmac_f32_e32 v194, v193, v192
	s_cmp_eq_u32 s46, 2
	s_cbranch_scc1 .Lci_x1
	v_fmac_f32_e32 v196, v195, v194
	s_cmp_eq_u32 s46, 3
	s_cbranch_scc1 .Lci_x2
	v_fmac_f32_e32 v198, v197, v196
	s_cmp_eq_u32 s46, 4
	s_cbranch_scc1 .Lci_x3
	v_fmac_f32_e32 v200, v199, v198
	s_cmp_eq_u32 s46, 5
	s_cbranch_scc1 .Lci_x4
	v_fmac_f32_e32 v202, v201, v200
	s_cmp_eq_u32 s46, 6
	s_cbranch_scc1 .Lci_x5
	v_fmac_f32_e32 v204, v203, v202
	s_cmp_eq_u32 s46, 7
	s_cbranch_scc1 .Lci_x6
	v_fmac_f32_e32 v206, v205, v204
	s_cmp_eq_u32 s46, 8
	s_cbranch_scc1 .Lci_x7
	v_fmac_f32_e32 v208, v207, v206
	s_cmp_eq_u32 s46, 9
	s_cbranch_scc1 .Lci_x8
	v_fmac_f32_e32 v210, v209, v208
	s_cmp_eq_u32 s46, 10
	s_cbranch_scc1 .Lci_x9
	v_fmac_f32_e32 v212, v211, v210
	s_cmp_eq_u32 s46, 11
	s_cbranch_scc1 .Lci_x10
	v_fmac_f32_e32 v214, v213, v212
	s_cmp_eq_u32 s46, 12
	s_cbranch_scc1 .Lci_x11
	v_fmac_f32_e32 v216, v215, v214
	s_cmp_eq_u32 s46, 13
	s_cbranch_scc1 .Lci_x12
	v_fmac_f32_e32 v218, v217, v216
	s_cmp_eq_u32 s46, 14
	s_cbranch_scc1 .Lci_x13
	v_fmac_f32_e32 v220, v219, v218
	s_cmp_eq_u32 s46, 15
	s_cbranch_scc1 .Lci_x14
	v_fmac_f32_e32 v222, v221, v220
	s_cmp_eq_u32 s46, 16
	s_cbranch_scc1 .Lci_x15
	v_fmac_f32_e32 v224, v223, v222
	s_cmp_eq_u32 s46, 17
	s_cbranch_scc1 .Lci_x16
	v_fmac_f32_e32 v226, v225, v224
	s_cmp_eq_u32 s46, 18
	s_cbranch_scc1 .Lci_x17
	v_fmac_f32_e32 v228, v227, v226
	s_cmp_eq_u32 s46, 19
	s_cbranch_scc1 .Lci_x18
	v_fmac_f32_e32 v230, v229, v228
	s_cmp_eq_u32 s46, 20
	s_cbranch_scc1 .Lci_x19
	v_fmac_f32_e32 v232, v231, v230
	s_cmp_eq_u32 s46, 21
	s_cbranch_scc1 .Lci_x20
	v_fmac_f32_e32 v234, v233, v232
	s_cmp_eq_u32 s46, 22
	s_cbranch_scc1 .Lci_x21
	v_fmac_f32_e32 v236, v235, v234
	s_cmp_eq_u32 s46, 23
	s_cbranch_scc1 .Lci_x22
	v_fmac_f32_e32 v238, v237, v236
	s_cmp_eq_u32 s46, 24
	s_cbranch_scc1 .Lci_x23
	v_fmac_f32_e32 v240, v239, v238
	s_cmp_eq_u32 s46, 25
	s_cbranch_scc1 .Lci_x24
	v_fmac_f32_e32 v242, v241, v240
	s_cmp_eq_u32 s46, 26
	s_cbranch_scc1 .Lci_x25
	v_fmac_f32_e32 v8, v243, v242
	s_cmp_eq_u32 s46, 27
	s_cbranch_scc1 .Lci_x26
	v_fmac_f32_e32 v248, v247, v8
	s_cmp_eq_u32 s46, 28
	s_cbranch_scc1 .Lci_x27
	v_fmac_f32_e32 v250, v249, v248
	s_cmp_eq_u32 s46, 29
	s_cbranch_scc1 .Lci_x28
	v_fmac_f32_e32 v252, v251, v250
	s_cmp_eq_u32 s46, 30
	s_cbranch_scc1 .Lci_x29
	v_fmac_f32_e32 v255, v253, v252
	v_mov_b32_e32 v111, v255
	s_branch .LBB0_461
.Lci_x0:
	v_mov_b32_e32 v111, v192
	s_branch .LBB0_461
.Lci_x1:
	v_mov_b32_e32 v111, v194
	s_branch .LBB0_461
.Lci_x2:
	v_mov_b32_e32 v111, v196
	s_branch .LBB0_461
.Lci_x3:
	v_mov_b32_e32 v111, v198
	s_branch .LBB0_461
.Lci_x4:
	v_mov_b32_e32 v111, v200
	s_branch .LBB0_461
.Lci_x5:
	v_mov_b32_e32 v111, v202
	s_branch .LBB0_461
.Lci_x6:
	v_mov_b32_e32 v111, v204
	s_branch .LBB0_461
.Lci_x7:
	v_mov_b32_e32 v111, v206
	s_branch .LBB0_461
.Lci_x8:
	v_mov_b32_e32 v111, v208
	s_branch .LBB0_461
.Lci_x9:
	v_mov_b32_e32 v111, v210
	s_branch .LBB0_461
.Lci_x10:
	v_mov_b32_e32 v111, v212
	s_branch .LBB0_461
.Lci_x11:
	v_mov_b32_e32 v111, v214
	s_branch .LBB0_461
.Lci_x12:
	v_mov_b32_e32 v111, v216
	s_branch .LBB0_461
.Lci_x13:
	v_mov_b32_e32 v111, v218
	s_branch .LBB0_461
.Lci_x14:
	v_mov_b32_e32 v111, v220
	s_branch .LBB0_461
.Lci_x15:
	v_mov_b32_e32 v111, v222
	s_branch .LBB0_461
.Lci_x16:
	v_mov_b32_e32 v111, v224
	s_branch .LBB0_461
.Lci_x17:
	v_mov_b32_e32 v111, v226
	s_branch .LBB0_461
.Lci_x18:
	v_mov_b32_e32 v111, v228
	s_branch .LBB0_461
.Lci_x19:
	v_mov_b32_e32 v111, v230
	s_branch .LBB0_461
.Lci_x20:
	v_mov_b32_e32 v111, v232
	s_branch .LBB0_461
.Lci_x21:
	v_mov_b32_e32 v111, v234
	s_branch .LBB0_461
.Lci_x22:
	v_mov_b32_e32 v111, v236
	s_branch .LBB0_461
.Lci_x23:
	v_mov_b32_e32 v111, v238
	s_branch .LBB0_461
.Lci_x24:
	v_mov_b32_e32 v111, v240
	s_branch .LBB0_461
.Lci_x25:
	v_mov_b32_e32 v111, v242
	s_branch .LBB0_461
.Lci_x26:
	v_mov_b32_e32 v111, v8
	s_branch .LBB0_461
.Lci_x27:
	v_mov_b32_e32 v111, v248
	s_branch .LBB0_461
.Lci_x28:
	v_mov_b32_e32 v111, v250
	s_branch .LBB0_461
.Lci_x29:
	v_mov_b32_e32 v111, v252
	s_branch .LBB0_461
